# attention 64-dim main loop: softmax block rewritten by hand (in-place exps, plain f32 adds in 4 partial sums, no packed moves)
# speedup vs baseline: 1.0478x; 1.0259x over previous
.LBB0_338:
	v_exp_f32_e32 v64, v64
	v_exp_f32_e32 v136, v48
	v_exp_f32_e32 v65, v65
	v_exp_f32_e32 v137, v49
	v_exp_f32_e32 v66, v66
	v_exp_f32_e32 v138, v50
	v_exp_f32_e32 v67, v67
	v_exp_f32_e32 v139, v51
	s_cmp_eq_u32 s98, 0
	s_cbranch_scc1 .Lstg_x_3
	s_waitcnt lgkmcnt(0)
	s_barrier
.Lstg_x_3:
	v_exp_f32_e32 v68, v68
	v_exp_f32_e32 v140, v52
	v_exp_f32_e32 v69, v69
	v_exp_f32_e32 v141, v53
	v_add_f32_e32 v152, v64, v136
	v_add_f32_e32 v153, v65, v137
	v_add_f32_e32 v154, v66, v138
	v_add_f32_e32 v155, v67, v139
	v_exp_f32_e32 v70, v70
	v_exp_f32_e32 v142, v54
	v_exp_f32_e32 v71, v71
	v_exp_f32_e32 v143, v55
	v_add_f32_e32 v152, v152, v68
	v_add_f32_e32 v153, v153, v140
	v_add_f32_e32 v154, v154, v69
	v_add_f32_e32 v155, v155, v141
	v_exp_f32_e32 v72, v72
	v_exp_f32_e32 v144, v56
	v_exp_f32_e32 v73, v73
	v_exp_f32_e32 v145, v57
	v_add_f32_e32 v152, v152, v70
	v_add_f32_e32 v153, v153, v142
	v_add_f32_e32 v154, v154, v71
	v_add_f32_e32 v155, v155, v143
	v_exp_f32_e32 v74, v74
	v_exp_f32_e32 v146, v58
	v_exp_f32_e32 v75, v75
	v_exp_f32_e32 v147, v59
	v_add_f32_e32 v152, v152, v72
	v_add_f32_e32 v153, v153, v144
	v_add_f32_e32 v154, v154, v73
	v_add_f32_e32 v155, v155, v145
	v_exp_f32_e32 v76, v76
	v_exp_f32_e32 v148, v60
	v_exp_f32_e32 v77, v77
	v_exp_f32_e32 v149, v61
	v_add_f32_e32 v152, v152, v74
	v_add_f32_e32 v153, v153, v146
	v_add_f32_e32 v154, v154, v75
	v_add_f32_e32 v155, v155, v147
	v_exp_f32_e32 v78, v78
	v_exp_f32_e32 v150, v62
	v_exp_f32_e32 v79, v79
	v_exp_f32_e32 v151, v63
	v_add_f32_e32 v152, v152, v76
	v_add_f32_e32 v153, v153, v148
	v_add_f32_e32 v154, v154, v77
	v_add_f32_e32 v155, v155, v149
	v_cvt_pk_bf16_f32 v48, v64, v65
	v_cvt_pk_bf16_f32 v49, v66, v67
	v_add_f32_e32 v152, v152, v78
	v_add_f32_e32 v153, v153, v150
	v_add_f32_e32 v154, v154, v79
	v_add_f32_e32 v155, v155, v151
	v_cvt_pk_bf16_f32 v50, v68, v69
	v_cvt_pk_bf16_f32 v51, v70, v71
	v_cvt_pk_bf16_f32 v52, v72, v73
	v_cvt_pk_bf16_f32 v53, v74, v75
	v_cvt_pk_bf16_f32 v54, v76, v77
	v_cvt_pk_bf16_f32 v55, v78, v79
	v_add_f32_e32 v152, v152, v153
	v_add_f32_e32 v154, v154, v155
	v_cvt_pk_bf16_f32 v56, v136, v137
	v_cvt_pk_bf16_f32 v57, v138, v139
	v_cvt_pk_bf16_f32 v58, v140, v141
	v_cvt_pk_bf16_f32 v59, v142, v143
	v_add_f32_e32 v152, v152, v154
	v_cvt_pk_bf16_f32 v60, v144, v145
	v_cvt_pk_bf16_f32 v61, v146, v147
	v_cvt_pk_bf16_f32 v62, v148, v149
	v_cvt_pk_bf16_f32 v63, v150, v151
	v_add_f32_e32 v194, v194, v152
	s_setprio 1
	s_cmp_lg_u32 s98, 0
	s_cbranch_scc1 .Lstg_y_4
	s_waitcnt lgkmcnt(0)
	s_barrier
